# n1 + diff loop: the three next-tile pointer advances (64-bit VALU) moved from the loop tail into the idle slots after the last QK MFMA (MFMA-shadow fill)
# baseline (speedup 1.0000x reference)
; template <int DK, int MODE, bool OUTF32> ...
;     ...
;     for (int t = t_lo; t < t_hi; ++t) {
;         const int cur = (t - t_lo) & 1;
;         if (t + 1 < t_hi) A_ISSUE(t + 1);
.LBB0_942:
	s_or_b64 exec, exec, s[50:51]
	s_xor_b32 s13, s13, 1
	s_mulk_i32 s13, 0x4400
	s_add_i32 s13, s13, 0
	v_add3_u32 v68, s13, v188, v189
	s_waitcnt vmcnt(3)
	ds_write_b128 v68, v[120:123]
	v_add3_u32 v68, s13, v190, v191
	s_waitcnt vmcnt(2)
	ds_write_b128 v68, v[116:119]
	v_add_u32_e32 v68, s13, v185
	s_mov_b32 s14, 0xc800
	v_add3_u32 v68, v68, v170, s14
	s_add_i32 s12, s12, 1
	s_waitcnt vmcnt(1)
	ds_write2_b64 v68, v[128:129], v[130:131] offset1:1
	v_add_u32_e32 v68, s13, v186
	v_add3_u32 v68, v68, v170, s14
	s_mov_b64 s[14:15], 0x4000
	v_cmp_eq_u32_e32 vcc, s12, v182
	s_or_b64 s[42:43], vcc, s[42:43]
	s_mov_b64 s[10:11], 0x4000
	s_waitcnt vmcnt(0)
	ds_write2_b64 v68, v[124:125], v[126:127] offset1:1
	s_and_b32 s13, s12, 1
	s_mul_i32 s14, s13, 0x4400
	v_add_u32_e32 v242, s14, v183
	v_add_u32_e32 v196, s14, v184
	s_waitcnt lgkmcnt(0)
	s_andn2_b64 exec, exec, s[42:43]
	s_cbranch_execz .Ldq_exit

; template <int DK, int MODE, bool OUTF32> ...
;     ...
;     for (int t = t_lo; t < t_hi; ++t) {
;         const int cur = (t - t_lo) & 1;
;         if (t + 1 < t_hi) A_ISSUE(t + 1);
;         bool act;
;         if (MODE == 0) act = (64 * t + 32 * kh) <= (qw0 + 31);
;         else if (MODE == 1) act = (t <= cw) && (t >= cw - 8);
;         else act = (t <= cw);
;         if (act) {
;             f32x16 p;
; #pragma unroll
;             for (int r = 0; r < 16; ++r) p[r] = 0.f;
;             const unsigned char* kb = a_lds + cur * KBUF + (32 * kh + c) * KP + hi * 16;
;             constexpr bool HOISTK = true;
;             bf16x8 kf[NKS];
;             if (HOISTK) {
; #pragma unroll
;                 for (int s = 0; s < NKS; ++s) kf[s] = *(const bf16x8*)(kb + s * 32);
;             }
;             const unsigned char* vb = a_lds + OFF_V + cur * VBUF + c * VP + (32 * kh + 4 * hi) * 2;
;             bf16x8 vf[8];
;     ...
;             constexpr bool HOISTV = (DK == 128) && (MODE == 2 || MODE == 1);
;             if (HOISTV) A_VREADS(0, 3);
;             if (HOISTK) __builtin_amdgcn_sched_barrier(0);
; #pragma unroll
;             for (int s = 0; s < NKS; ++s) p = __builtin_amdgcn_mfma_f32_32x32x16_bf16(HOISTK ? kf[s] : *(const bf16x8*)(kb + s * 32), qf[s], p, 0, 0, 0);
;             if (HOISTV) { A_VREADS(3, 4); __builtin_amdgcn_sched_barrier(0); }
;             if (MODE == 0) {
;                 const float* ckp = (const float*)(a_lds + OFF_CK + cur * 256) + 32 * kh + 4 * hi;
; #pragma unroll
;                 for (int g = 0; g < 4; ++g) {
;                     const float4 ck = *(const float4*)(ckp + 8 * g);
;                     p[4 * g + 0] = fmaf(p[4 * g + 0], sc2, cq - ck.x); p[4 * g + 1] = fmaf(p[4 * g + 1], sc2, cq - ck.y);
;                     p[4 * g + 2] = fmaf(p[4 * g + 2], sc2, cq - ck.z); p[4 * g + 3] = fmaf(p[4 * g + 3], sc2, cq - ck.w);
;                 }
;                 if (64 * t + 32 * kh + 31 > qw0) {
;                     const int kbase = 64 * t + 32 * kh + 4 * hi;
; #pragma unroll
;                     for (int r = 0; r < 16; ++r) if (kbase + (r & 3) + 8 * (r >> 2) > qrow) p[r] = NEGINF;
;                 }
;             } else if (MODE == 1) {
;                 const float* rb = (const float*)(a_lds + OFF_RB);
;                 if (t <= cw - 3) {
;                     const float bb = rb[256];
; #pragma unroll
.LBB0_943:
	v_cmp_le_i32_e32 vcc, s12, v187
	s_and_saveexec_b64 s[50:51], vcc
	s_cbranch_execz .Ldiff_inact
	ds_read_b128 v[68:71], v242
	ds_read_b128 v[156:159], v242 offset:32
	ds_read_b128 v[160:163], v242 offset:64
	ds_read_b128 v[192:195], v242 offset:96
	ds_read_b128 v[208:211], v242 offset:128
	ds_read_b128 v[212:215], v242 offset:160
	ds_read_b128 v[216:219], v242 offset:192
	ds_read_b128 v[220:223], v242 offset:224
	v_add_u32_e32 v72, 0xc800, v196
	ds_read2_b64 v[132:135], v72 offset1:2
	ds_read2_b64 v[136:139], v72 offset0:4 offset1:6
	v_add_u32_e32 v72, 0xd800, v196
	ds_read2_b64 v[140:143], v72 offset0:32 offset1:34
	ds_read2_b64 v[144:147], v72 offset0:36 offset1:38
	v_add_u32_e32 v72, 0xe800, v196
	ds_read2_b64 v[148:151], v72 offset0:64 offset1:66
	ds_read2_b64 v[152:155], v72 offset0:68 offset1:70
	v_add_co_u32_e32 v240, vcc, 0xfff80000, v172
	global_load_dwordx4 v[120:123], v[174:175], off
	global_load_dwordx4 v[116:119], v[176:177], off
	v_addc_co_u32_e32 v241, vcc, -1, v173, vcc
	global_load_dwordx4 v[128:131], v[240:241], off
	global_load_dwordx4 v[124:127], v[172:173], off
	s_waitcnt lgkmcnt(13)
	v_mfma_f32_32x32x16_bf16 v[68:83], v[68:71], v[112:115], 0
	s_waitcnt lgkmcnt(12)
	v_mfma_f32_32x32x16_bf16 v[68:83], v[156:159], v[108:111], v[68:83]
	v_add_u32_e32 v156, 0xf800, v196
	s_waitcnt lgkmcnt(11)
	v_mfma_f32_32x32x16_bf16 v[68:83], v[160:163], v[104:107], v[68:83]
	ds_read2_b64 v[160:163], v156 offset0:96 offset1:98
	ds_read2_b64 v[156:159], v156 offset0:100 offset1:102
	s_waitcnt lgkmcnt(12)
	v_mfma_f32_32x32x16_bf16 v[68:83], v[192:195], v[100:103], v[68:83]
	s_waitcnt lgkmcnt(11)
	v_mfma_f32_32x32x16_bf16 v[68:83], v[208:211], v[96:99], v[68:83]
	s_waitcnt lgkmcnt(10)
	v_mfma_f32_32x32x16_bf16 v[68:83], v[212:215], v[92:95], v[68:83]
	s_waitcnt lgkmcnt(9)
	v_mfma_f32_32x32x16_bf16 v[68:83], v[216:219], v[88:91], v[68:83]
	s_waitcnt lgkmcnt(8)
	v_mfma_f32_32x32x16_bf16 v[68:83], v[220:223], v[84:87], v[68:83]
	s_mov_b64 s[14:15], 0x4000
	v_lshl_add_u64 v[172:173], v[172:173], 0, s[88:89]
	v_lshl_add_u64 v[176:177], v[176:177], 0, s[14:15]
	v_lshl_add_u64 v[174:175], v[174:175], 0, s[14:15]
	s_nop 7
	v_max_f32_e32 v192, v69, v69
	v_max_f32_e32 v193, v68, v68
	v_max_f32_e32 v192, v193, v192
	v_max3_f32 v192, v192, v70, v71
	v_max3_f32 v192, v192, v72, v73
	v_max3_f32 v192, v192, v74, v75
	v_max3_f32 v192, v192, v76, v77
	v_max3_f32 v192, v192, v78, v79
	v_max3_f32 v192, v192, v80, v81
	v_max3_f32 v192, v192, v82, v83
	v_mul_f32_e32 v192, 0x3e0293ee, v192
	v_mov_b32_e32 v193, v192
	s_nop 1
	v_permlane32_swap_b32_e32 v192, v193
	v_max_f32_e32 v193, v193, v193
	v_max_f32_e32 v192, v192, v192
	v_max_f32_e32 v192, v192, v193
	v_sub_f32_e32 v193, v192, v181
	s_mov_b32 s14, 0x41000000
	v_cmp_ge_f32_e32 vcc, s14, v193
	s_cmp_eq_u64 vcc, exec
	s_cbranch_scc1 .LBB0_941
	v_max_f32_e32 v192, v192, v192
	v_max_f32_e32 v193, v181, v181
	v_max_f32_e32 v193, v193, v192
	v_sub_f32_e32 v181, v181, v193
	v_exp_f32_e32 v192, v181
	v_mov_b32_e32 v181, v193
	v_pk_mul_f32 v[66:67], v[66:67], v[192:193] op_sel_hi:[1,0]
	v_pk_mul_f32 v[64:65], v[64:65], v[192:193] op_sel_hi:[1,0]
	v_pk_mul_f32 v[62:63], v[62:63], v[192:193] op_sel_hi:[1,0]
	v_pk_mul_f32 v[60:61], v[60:61], v[192:193] op_sel_hi:[1,0]
	v_pk_mul_f32 v[58:59], v[58:59], v[192:193] op_sel_hi:[1,0]
	v_pk_mul_f32 v[56:57], v[56:57], v[192:193] op_sel_hi:[1,0]
	v_pk_mul_f32 v[54:55], v[54:55], v[192:193] op_sel_hi:[1,0]
	v_pk_mul_f32 v[52:53], v[52:53], v[192:193] op_sel_hi:[1,0]
	v_pk_mul_f32 v[34:35], v[34:35], v[192:193] op_sel_hi:[1,0]
	v_pk_mul_f32 v[32:33], v[32:33], v[192:193] op_sel_hi:[1,0]
	v_pk_mul_f32 v[30:31], v[30:31], v[192:193] op_sel_hi:[1,0]
	v_pk_mul_f32 v[28:29], v[28:29], v[192:193] op_sel_hi:[1,0]
	v_pk_mul_f32 v[26:27], v[26:27], v[192:193] op_sel_hi:[1,0]
	v_pk_mul_f32 v[24:25], v[24:25], v[192:193] op_sel_hi:[1,0]
	v_pk_mul_f32 v[22:23], v[22:23], v[192:193] op_sel_hi:[1,0]
	v_pk_mul_f32 v[20:21], v[20:21], v[192:193] op_sel_hi:[1,0]
	v_pk_mul_f32 v[50:51], v[50:51], v[192:193] op_sel_hi:[1,0]
	v_pk_mul_f32 v[48:49], v[48:49], v[192:193] op_sel_hi:[1,0]
	v_pk_mul_f32 v[46:47], v[46:47], v[192:193] op_sel_hi:[1,0]
	v_pk_mul_f32 v[44:45], v[44:45], v[192:193] op_sel_hi:[1,0]
	v_pk_mul_f32 v[42:43], v[42:43], v[192:193] op_sel_hi:[1,0]
	v_pk_mul_f32 v[40:41], v[40:41], v[192:193] op_sel_hi:[1,0]
	v_pk_mul_f32 v[38:39], v[38:39], v[192:193] op_sel_hi:[1,0]
	v_pk_mul_f32 v[36:37], v[36:37], v[192:193] op_sel_hi:[1,0]
	v_pk_mul_f32 v[18:19], v[18:19], v[192:193] op_sel_hi:[1,0]
	v_pk_mul_f32 v[16:17], v[16:17], v[192:193] op_sel_hi:[1,0]
	v_pk_mul_f32 v[14:15], v[14:15], v[192:193] op_sel_hi:[1,0]
	v_pk_mul_f32 v[12:13], v[12:13], v[192:193] op_sel_hi:[1,0]
	v_pk_mul_f32 v[10:11], v[10:11], v[192:193] op_sel_hi:[1,0]
	v_pk_mul_f32 v[8:9], v[8:9], v[192:193] op_sel_hi:[1,0]
	v_pk_mul_f32 v[6:7], v[6:7], v[192:193] op_sel_hi:[1,0]
	v_pk_mul_f32 v[4:5], v[4:5], v[192:193] op_sel_hi:[1,0]
	v_mul_f32_e32 v179, v179, v192
	s_branch .LBB0_941

.Ldiff_inact:
	s_or_b64 exec, exec, s[50:51]
	s_mov_b64 s[14:15], 0x4000
	v_lshl_add_u64 v[172:173], v[172:173], 0, s[88:89]
	v_lshl_add_u64 v[176:177], v[176:177], 0, s[14:15]
	v_lshl_add_u64 v[174:175], v[174:175], 0, s[14:15]
	v_add_co_u32_e32 v240, vcc, 0xfff80000, v172
	global_load_dwordx4 v[120:123], v[174:175], off
	global_load_dwordx4 v[116:119], v[176:177], off
	v_addc_co_u32_e32 v241, vcc, -1, v173, vcc
	global_load_dwordx4 v[128:131], v[240:241], off
	global_load_dwordx4 v[124:127], v[172:173], off
	s_branch .LBB0_942
